# GEMM K-loops: first iteration peeled with C=0 on each accumulator's first MFMA, accumulator zeroing removed
# speedup vs baseline: 1.0096x; 1.0014x over previous
.LBB0_134:
	s_ashr_i32 s47, s46, 31
	s_lshl_b64 s[6:7], s[46:47], 19
	s_add_u32 s48, s92, s6
	s_addc_u32 s49, s93, s7
	s_and_b64 s[6:7], s[38:39], exec
	s_cselect_b32 s47, s49, s53
	s_cselect_b32 s68, s48, s52
	s_ashr_i32 s45, s44, 31
	s_lshl_b64 s[6:7], s[44:45], 19
	s_add_u32 s50, s58, s6
	s_addc_u32 s51, s59, s7
	s_and_b64 s[6:7], s[38:39], exec
	s_cselect_b32 s45, s51, s55
	s_cselect_b32 s69, s50, s54
	s_add_u32 s52, s52, 0x40080
	s_addc_u32 s53, s53, 0
	s_add_u32 s70, s54, 0x100
	s_addc_u32 s71, s55, 0
	s_mov_b32 s72, -2
	s_waitcnt vmcnt(0)
	s_add_u32 s6, s52, 0xfffc0080
	s_addc_u32 s7, s53, -1
	s_add_i32 s24, 0, 0x10000
	s_cmp_eq_u32 s72, 12
	s_cselect_b32 s57, s47, s7
	s_cselect_b32 s56, s68, s6
	v_add_u32_e32 v148, s24, v151
	s_cselect_b32 s55, s45, s71
	s_cselect_b32 s54, s69, s70
	s_add_i32 s25, 0, 0x14000
	ds_read_b128 v[140:143], v148
	ds_read_b128 v[144:147], v148 offset:1024
	ds_read_b128 v[156:159], v148 offset:2048
	ds_read_b128 v[160:163], v148 offset:3072
	v_add_u32_e32 v148, s25, v151
	ds_read_b128 v[164:167], v148
	ds_read_b128 v[168:171], v148 offset:1024
	ds_read_b128 v[172:175], v148 offset:2048
	ds_read_b128 v[176:179], v148 offset:3072
	v_lshl_add_u64 v[148:149], s[52:53], 0, v[136:137]
	s_add_i32 m0, s61, 0xc000
	ds_read_b128 v[180:183], v154
	ds_read_b128 v[184:187], v154 offset:1024
	ds_read_b128 v[188:191], v154 offset:2048
	ds_read_b128 v[192:195], v154 offset:3072
	ds_read_b128 v[196:199], v154 offset:4096
	ds_read_b128 v[200:203], v154 offset:5120
	ds_read_b128 v[204:207], v154 offset:6144
	ds_read_b128 v[208:211], v154 offset:7168
	global_load_lds_dwordx4 v[148:149], off
	v_lshl_add_u64 v[148:149], s[52:53], 0, v[138:139]
	s_add_i32 m0, s61, 0xe000
	s_nop 0
	global_load_lds_dwordx4 v[148:149], off
	s_waitcnt vmcnt(8)
	s_waitcnt lgkmcnt(0)
	s_barrier
	s_setprio 1
	s_waitcnt lgkmcnt(0)
	v_mfma_f32_16x16x32_bf16 v[126:129], v[140:143], v[180:183], 0
	v_mfma_f32_16x16x32_bf16 v[122:125], v[156:159], v[180:183], 0
	v_mfma_f32_16x16x32_bf16 v[110:113], v[140:143], v[188:191], 0
	v_mfma_f32_16x16x32_bf16 v[106:109], v[156:159], v[188:191], 0
	v_mfma_f32_16x16x32_bf16 v[94:97], v[140:143], v[196:199], 0
	v_mfma_f32_16x16x32_bf16 v[90:93], v[156:159], v[196:199], 0
	v_mfma_f32_16x16x32_bf16 v[78:81], v[140:143], v[204:207], 0
	v_mfma_f32_16x16x32_bf16 v[74:77], v[156:159], v[204:207], 0
	v_mfma_f32_16x16x32_bf16 v[126:129], v[144:147], v[184:187], v[126:129]
	v_mfma_f32_16x16x32_bf16 v[122:125], v[160:163], v[184:187], v[122:125]
	v_mfma_f32_16x16x32_bf16 v[110:113], v[144:147], v[192:195], v[110:113]
	v_mfma_f32_16x16x32_bf16 v[106:109], v[160:163], v[192:195], v[106:109]
	v_mfma_f32_16x16x32_bf16 v[94:97], v[144:147], v[200:203], v[94:97]
	v_mfma_f32_16x16x32_bf16 v[90:93], v[160:163], v[200:203], v[90:93]
	v_mfma_f32_16x16x32_bf16 v[78:81], v[144:147], v[208:211], v[78:81]
	v_mfma_f32_16x16x32_bf16 v[74:77], v[160:163], v[208:211], v[74:77]
	s_setprio 0
	s_setprio 1
	v_mfma_f32_16x16x32_bf16 v[118:121], v[164:167], v[180:183], 0
	v_mfma_f32_16x16x32_bf16 v[114:117], v[172:175], v[180:183], 0
	v_mfma_f32_16x16x32_bf16 v[102:105], v[164:167], v[188:191], 0
	v_mfma_f32_16x16x32_bf16 v[98:101], v[172:175], v[188:191], 0
	v_mfma_f32_16x16x32_bf16 v[86:89], v[164:167], v[196:199], 0
	v_mfma_f32_16x16x32_bf16 v[82:85], v[172:175], v[196:199], 0
	v_mfma_f32_16x16x32_bf16 v[70:73], v[164:167], v[204:207], 0
	v_mfma_f32_16x16x32_bf16 v[66:69], v[172:175], v[204:207], 0
	v_mfma_f32_16x16x32_bf16 v[118:121], v[168:171], v[184:187], v[118:121]
	v_mfma_f32_16x16x32_bf16 v[114:117], v[176:179], v[184:187], v[114:117]
	v_mfma_f32_16x16x32_bf16 v[102:105], v[168:171], v[192:195], v[102:105]
	v_mfma_f32_16x16x32_bf16 v[98:101], v[176:179], v[192:195], v[98:101]
	v_mfma_f32_16x16x32_bf16 v[86:89], v[168:171], v[200:203], v[86:89]
	v_mfma_f32_16x16x32_bf16 v[82:85], v[176:179], v[200:203], v[82:85]
	v_mfma_f32_16x16x32_bf16 v[70:73], v[168:171], v[208:211], v[70:73]
	v_mfma_f32_16x16x32_bf16 v[66:69], v[176:179], v[208:211], v[66:69]
	s_setprio 0
	s_barrier
	s_add_i32 s6, s24, s60
	v_lshl_add_u64 v[148:149], s[54:55], 0, v[0:1]
	s_mov_b32 m0, s6
	ds_read_b128 v[180:183], v154 offset:16384
	ds_read_b128 v[184:187], v154 offset:17408
	ds_read_b128 v[188:191], v154 offset:18432
	ds_read_b128 v[192:195], v154 offset:19456
	ds_read_b128 v[196:199], v154 offset:20480
	ds_read_b128 v[200:203], v154 offset:21504
	ds_read_b128 v[204:207], v154 offset:22528
	ds_read_b128 v[208:211], v154 offset:23552
	global_load_lds_dwordx4 v[148:149], off
	s_add_i32 m0, s6, 0x2000
	s_add_u32 s6, s54, 0x40000
	v_lshl_add_u64 v[212:213], s[54:55], 0, v[130:131]
	s_addc_u32 s7, s55, 0
	s_add_i32 s24, s25, s60
	global_load_lds_dwordx4 v[212:213], off
	v_lshl_add_u64 v[214:215], s[6:7], 0, v[0:1]
	s_mov_b32 m0, s24
	v_lshl_add_u64 v[216:217], s[56:57], 0, v[132:133]
	global_load_lds_dwordx4 v[214:215], off
	v_lshl_add_u64 v[214:215], s[6:7], 0, v[130:131]
	s_add_i32 m0, s24, 0x2000
	s_nop 0
	global_load_lds_dwordx4 v[214:215], off
	v_lshl_add_u64 v[214:215], s[56:57], 0, v[134:135]
	s_mov_b32 m0, s61
	s_nop 0
	global_load_lds_dwordx4 v[214:215], off
	s_mov_b32 m0, s62
	s_nop 0
	global_load_lds_dwordx4 v[216:217], off
	s_waitcnt vmcnt(8)
	s_waitcnt lgkmcnt(0)
	s_barrier
	s_setprio 1
	s_waitcnt lgkmcnt(0)
	v_mfma_f32_16x16x32_bf16 v[62:65], v[140:143], v[180:183], 0
	v_mfma_f32_16x16x32_bf16 v[58:61], v[156:159], v[180:183], 0
	v_mfma_f32_16x16x32_bf16 v[46:49], v[140:143], v[188:191], 0
	v_mfma_f32_16x16x32_bf16 v[42:45], v[156:159], v[188:191], 0
	v_mfma_f32_16x16x32_bf16 v[30:33], v[140:143], v[196:199], 0
	v_mfma_f32_16x16x32_bf16 v[26:29], v[156:159], v[196:199], 0
	v_mfma_f32_16x16x32_bf16 v[14:17], v[140:143], v[204:207], 0
	v_mfma_f32_16x16x32_bf16 v[10:13], v[156:159], v[204:207], 0
	v_mfma_f32_16x16x32_bf16 v[62:65], v[144:147], v[184:187], v[62:65]
	v_mfma_f32_16x16x32_bf16 v[58:61], v[160:163], v[184:187], v[58:61]
	v_mfma_f32_16x16x32_bf16 v[46:49], v[144:147], v[192:195], v[46:49]
	v_mfma_f32_16x16x32_bf16 v[42:45], v[160:163], v[192:195], v[42:45]
	v_mfma_f32_16x16x32_bf16 v[30:33], v[144:147], v[200:203], v[30:33]
	v_mfma_f32_16x16x32_bf16 v[26:29], v[160:163], v[200:203], v[26:29]
	v_mfma_f32_16x16x32_bf16 v[14:17], v[144:147], v[208:211], v[14:17]
	v_mfma_f32_16x16x32_bf16 v[10:13], v[160:163], v[208:211], v[10:13]
	s_setprio 0
	s_setprio 1
	v_mfma_f32_16x16x32_bf16 v[54:57], v[164:167], v[180:183], 0
	v_mfma_f32_16x16x32_bf16 v[50:53], v[172:175], v[180:183], 0
	v_mfma_f32_16x16x32_bf16 v[38:41], v[164:167], v[188:191], 0
	v_mfma_f32_16x16x32_bf16 v[34:37], v[172:175], v[188:191], 0
	v_mfma_f32_16x16x32_bf16 v[22:25], v[164:167], v[196:199], 0
	v_mfma_f32_16x16x32_bf16 v[18:21], v[172:175], v[196:199], 0
	v_mfma_f32_16x16x32_bf16 v[6:9], v[164:167], v[204:207], 0
	v_mfma_f32_16x16x32_bf16 v[2:5], v[172:175], v[204:207], 0
	v_mfma_f32_16x16x32_bf16 v[54:57], v[168:171], v[184:187], v[54:57]
	v_mfma_f32_16x16x32_bf16 v[50:53], v[176:179], v[184:187], v[50:53]
	v_mfma_f32_16x16x32_bf16 v[38:41], v[168:171], v[192:195], v[38:41]
	v_mfma_f32_16x16x32_bf16 v[34:37], v[176:179], v[192:195], v[34:37]
	v_mfma_f32_16x16x32_bf16 v[22:25], v[168:171], v[200:203], v[22:25]
	v_mfma_f32_16x16x32_bf16 v[18:21], v[176:179], v[200:203], v[18:21]
	v_mfma_f32_16x16x32_bf16 v[6:9], v[168:171], v[208:211], v[6:9]
	v_mfma_f32_16x16x32_bf16 v[2:5], v[176:179], v[208:211], v[2:5]
	s_setprio 0
	s_barrier
	s_add_i32 s24, 0, 0x18000
	v_add_u32_e32 v155, s24, v151
	s_add_i32 s25, 0, 0x1c000
	ds_read_b128 v[140:143], v155
	ds_read_b128 v[144:147], v155 offset:1024
	ds_read_b128 v[156:159], v155 offset:2048
	ds_read_b128 v[160:163], v155 offset:3072
	v_add_u32_e32 v155, s25, v151
	ds_read_b128 v[164:167], v155
	ds_read_b128 v[168:171], v155 offset:1024
	ds_read_b128 v[172:175], v155 offset:2048
	ds_read_b128 v[176:179], v155 offset:3072
	s_add_u32 s6, s56, 0x40000
	s_addc_u32 s7, s57, 0
	s_mov_b32 m0, s63
	v_lshl_add_u64 v[218:219], s[6:7], 0, v[134:135]
	ds_read_b128 v[180:183], v154 offset:32768
	ds_read_b128 v[184:187], v154 offset:33792
	ds_read_b128 v[188:191], v154 offset:34816
	ds_read_b128 v[192:195], v154 offset:35840
	ds_read_b128 v[196:199], v154 offset:36864
	ds_read_b128 v[200:203], v154 offset:37888
	ds_read_b128 v[204:207], v154 offset:38912
	ds_read_b128 v[208:211], v154 offset:39936
	global_load_lds_dwordx4 v[218:219], off
	v_lshl_add_u64 v[218:219], s[6:7], 0, v[132:133]
	s_mov_b32 m0, s64
	s_nop 0
	global_load_lds_dwordx4 v[218:219], off
	s_waitcnt vmcnt(8)
	s_waitcnt lgkmcnt(0)
	s_barrier
	s_setprio 1
	s_waitcnt lgkmcnt(0)
	v_mfma_f32_16x16x32_bf16 v[126:129], v[140:143], v[180:183], v[126:129]
	v_mfma_f32_16x16x32_bf16 v[122:125], v[156:159], v[180:183], v[122:125]
	v_mfma_f32_16x16x32_bf16 v[110:113], v[140:143], v[188:191], v[110:113]
	v_mfma_f32_16x16x32_bf16 v[106:109], v[156:159], v[188:191], v[106:109]
	v_mfma_f32_16x16x32_bf16 v[94:97], v[140:143], v[196:199], v[94:97]
	v_mfma_f32_16x16x32_bf16 v[90:93], v[156:159], v[196:199], v[90:93]
	v_mfma_f32_16x16x32_bf16 v[78:81], v[140:143], v[204:207], v[78:81]
	v_mfma_f32_16x16x32_bf16 v[74:77], v[156:159], v[204:207], v[74:77]
	v_mfma_f32_16x16x32_bf16 v[126:129], v[144:147], v[184:187], v[126:129]
	v_mfma_f32_16x16x32_bf16 v[122:125], v[160:163], v[184:187], v[122:125]
	v_mfma_f32_16x16x32_bf16 v[110:113], v[144:147], v[192:195], v[110:113]
	v_mfma_f32_16x16x32_bf16 v[106:109], v[160:163], v[192:195], v[106:109]
	v_mfma_f32_16x16x32_bf16 v[94:97], v[144:147], v[200:203], v[94:97]
	v_mfma_f32_16x16x32_bf16 v[90:93], v[160:163], v[200:203], v[90:93]
	v_mfma_f32_16x16x32_bf16 v[78:81], v[144:147], v[208:211], v[78:81]
	v_mfma_f32_16x16x32_bf16 v[74:77], v[160:163], v[208:211], v[74:77]
	s_setprio 0
	s_setprio 1
	v_mfma_f32_16x16x32_bf16 v[118:121], v[164:167], v[180:183], v[118:121]
	v_mfma_f32_16x16x32_bf16 v[114:117], v[172:175], v[180:183], v[114:117]
	v_mfma_f32_16x16x32_bf16 v[102:105], v[164:167], v[188:191], v[102:105]
	v_mfma_f32_16x16x32_bf16 v[98:101], v[172:175], v[188:191], v[98:101]
	v_mfma_f32_16x16x32_bf16 v[86:89], v[164:167], v[196:199], v[86:89]
	v_mfma_f32_16x16x32_bf16 v[82:85], v[172:175], v[196:199], v[82:85]
	v_mfma_f32_16x16x32_bf16 v[70:73], v[164:167], v[204:207], v[70:73]
	v_mfma_f32_16x16x32_bf16 v[66:69], v[172:175], v[204:207], v[66:69]
	v_mfma_f32_16x16x32_bf16 v[118:121], v[168:171], v[184:187], v[118:121]
	v_mfma_f32_16x16x32_bf16 v[114:117], v[176:179], v[184:187], v[114:117]
	v_mfma_f32_16x16x32_bf16 v[102:105], v[168:171], v[192:195], v[102:105]
	v_mfma_f32_16x16x32_bf16 v[98:101], v[176:179], v[192:195], v[98:101]
	v_mfma_f32_16x16x32_bf16 v[86:89], v[168:171], v[200:203], v[86:89]
	v_mfma_f32_16x16x32_bf16 v[82:85], v[176:179], v[200:203], v[82:85]
	v_mfma_f32_16x16x32_bf16 v[70:73], v[168:171], v[208:211], v[70:73]
	v_mfma_f32_16x16x32_bf16 v[66:69], v[176:179], v[208:211], v[66:69]
	s_setprio 0
	s_barrier
	s_add_i32 s6, s24, s60
	v_lshl_add_u64 v[148:149], v[148:149], 0, s[84:85]
	s_mov_b32 m0, s6
	ds_read_b128 v[180:183], v154 offset:49152
	ds_read_b128 v[184:187], v154 offset:50176
	ds_read_b128 v[188:191], v154 offset:51200
	ds_read_b128 v[192:195], v154 offset:52224
	ds_read_b128 v[196:199], v154 offset:53248
	ds_read_b128 v[200:203], v154 offset:54272
	ds_read_b128 v[204:207], v154 offset:55296
	ds_read_b128 v[208:211], v154 offset:56320
	global_load_lds_dwordx4 v[148:149], off
	s_add_i32 m0, s6, 0x2000
	s_add_u32 s6, s54, 0x40080
	v_lshl_add_u64 v[148:149], v[212:213], 0, s[84:85]
	s_addc_u32 s7, s55, 0
	s_add_i32 s24, s25, s60
	global_load_lds_dwordx4 v[148:149], off
	v_lshl_add_u64 v[148:149], s[6:7], 0, v[0:1]
	s_mov_b32 m0, s24
	s_nop 0
	global_load_lds_dwordx4 v[148:149], off
	v_lshl_add_u64 v[148:149], s[6:7], 0, v[130:131]
	s_add_i32 m0, s24, 0x2000
	s_nop 0
	global_load_lds_dwordx4 v[148:149], off
	v_lshl_add_u64 v[148:149], v[214:215], 0, s[84:85]
	s_mov_b32 m0, s65
	s_nop 0
	global_load_lds_dwordx4 v[148:149], off
	v_lshl_add_u64 v[148:149], v[216:217], 0, s[84:85]
	s_mov_b32 m0, s66
	s_nop 0
	global_load_lds_dwordx4 v[148:149], off
	s_waitcnt vmcnt(8)
	s_waitcnt lgkmcnt(0)
	s_barrier
	s_setprio 1
	s_waitcnt lgkmcnt(0)
	v_mfma_f32_16x16x32_bf16 v[62:65], v[140:143], v[180:183], v[62:65]
	v_mfma_f32_16x16x32_bf16 v[58:61], v[156:159], v[180:183], v[58:61]
	v_mfma_f32_16x16x32_bf16 v[46:49], v[140:143], v[188:191], v[46:49]
	v_mfma_f32_16x16x32_bf16 v[42:45], v[156:159], v[188:191], v[42:45]
	v_mfma_f32_16x16x32_bf16 v[30:33], v[140:143], v[196:199], v[30:33]
	v_mfma_f32_16x16x32_bf16 v[26:29], v[156:159], v[196:199], v[26:29]
	v_mfma_f32_16x16x32_bf16 v[14:17], v[140:143], v[204:207], v[14:17]
	v_mfma_f32_16x16x32_bf16 v[10:13], v[156:159], v[204:207], v[10:13]
	v_mfma_f32_16x16x32_bf16 v[62:65], v[144:147], v[184:187], v[62:65]
	v_mfma_f32_16x16x32_bf16 v[58:61], v[160:163], v[184:187], v[58:61]
	v_mfma_f32_16x16x32_bf16 v[46:49], v[144:147], v[192:195], v[46:49]
	v_mfma_f32_16x16x32_bf16 v[42:45], v[160:163], v[192:195], v[42:45]
	v_mfma_f32_16x16x32_bf16 v[30:33], v[144:147], v[200:203], v[30:33]
	v_mfma_f32_16x16x32_bf16 v[26:29], v[160:163], v[200:203], v[26:29]
	v_mfma_f32_16x16x32_bf16 v[14:17], v[144:147], v[208:211], v[14:17]
	v_mfma_f32_16x16x32_bf16 v[10:13], v[160:163], v[208:211], v[10:13]
	s_setprio 0
	s_setprio 1
	v_mfma_f32_16x16x32_bf16 v[54:57], v[164:167], v[180:183], v[54:57]
	v_mfma_f32_16x16x32_bf16 v[50:53], v[172:175], v[180:183], v[50:53]
	v_mfma_f32_16x16x32_bf16 v[38:41], v[164:167], v[188:191], v[38:41]
	v_mfma_f32_16x16x32_bf16 v[34:37], v[172:175], v[188:191], v[34:37]
	v_mfma_f32_16x16x32_bf16 v[22:25], v[164:167], v[196:199], v[22:25]
	v_mfma_f32_16x16x32_bf16 v[18:21], v[172:175], v[196:199], v[18:21]
	v_mfma_f32_16x16x32_bf16 v[6:9], v[164:167], v[204:207], v[6:9]
	v_mfma_f32_16x16x32_bf16 v[2:5], v[172:175], v[204:207], v[2:5]
	v_mfma_f32_16x16x32_bf16 v[54:57], v[168:171], v[184:187], v[54:57]
	v_mfma_f32_16x16x32_bf16 v[50:53], v[176:179], v[184:187], v[50:53]
	v_mfma_f32_16x16x32_bf16 v[38:41], v[168:171], v[192:195], v[38:41]
	v_mfma_f32_16x16x32_bf16 v[34:37], v[176:179], v[192:195], v[34:37]
	v_mfma_f32_16x16x32_bf16 v[22:25], v[168:171], v[200:203], v[22:25]
	v_mfma_f32_16x16x32_bf16 v[18:21], v[176:179], v[200:203], v[18:21]
	v_mfma_f32_16x16x32_bf16 v[6:9], v[168:171], v[208:211], v[6:9]
	v_mfma_f32_16x16x32_bf16 v[2:5], v[176:179], v[208:211], v[2:5]
	s_setprio 0
	s_barrier
	s_add_i32 s72, s72, 2
	s_add_u32 s52, s52, 0x100
	s_addc_u32 s53, s53, 0
	s_add_u32 s70, s70, 0x100
	s_addc_u32 s71, s71, 0
	s_cmp_gt_u32 s72, 13

.LBB0_230:
	s_ashr_i32 s53, s52, 31
	s_lshl_b64 s[24:25], s[52:53], 19
	s_add_u32 s54, s92, s24
	s_addc_u32 s55, s93, s25
	s_and_b64 s[24:25], s[38:39], exec
	s_cselect_b32 s37, s55, s1
	s_cselect_b32 s53, s54, s0
	s_ashr_i32 s51, s50, 31
	s_lshl_b64 s[24:25], s[50:51], 19
	s_add_u32 s56, s60, s24
	s_addc_u32 s57, s61, s25
	s_and_b64 s[24:25], s[38:39], exec
	s_cselect_b32 s51, s57, s41
	s_cselect_b32 s58, s56, s40
	s_add_u32 s0, s0, 0x40080
	s_addc_u32 s1, s1, 0
	s_add_u32 s59, s40, 0x100
	s_addc_u32 s70, s41, 0
	s_mov_b32 s71, -2
	s_add_u32 s6, s0, 0xfffc0080
	s_addc_u32 s7, s1, -1
	s_add_i32 s24, 0, 0x10000
	s_cmp_eq_u32 s71, 12
	s_cselect_b32 s43, s37, s7
	s_cselect_b32 s42, s53, s6
	v_add_u32_e32 v0, s24, v177
	s_cselect_b32 s41, s51, s70
	s_cselect_b32 s40, s58, s59
	s_add_i32 s6, 0, 0x14000
	ds_read_b128 v[10:13], v0
	ds_read_b128 v[14:17], v0 offset:1024
	ds_read_b128 v[26:29], v0 offset:2048
	ds_read_b128 v[30:33], v0 offset:3072
	v_add_u32_e32 v0, s6, v177
	ds_read_b128 v[146:149], v0
	ds_read_b128 v[150:153], v0 offset:1024
	ds_read_b128 v[166:169], v0 offset:2048
	ds_read_b128 v[170:173], v0 offset:3072
	v_lshl_add_u64 v[174:175], s[0:1], 0, v[162:163]
	s_add_i32 m0, s63, 0xc000
	ds_read_b128 v[182:185], v180
	ds_read_b128 v[186:189], v180 offset:1024
	ds_read_b128 v[190:193], v180 offset:2048
	ds_read_b128 v[194:197], v180 offset:3072
	ds_read_b128 v[198:201], v180 offset:4096
	ds_read_b128 v[202:205], v180 offset:5120
	ds_read_b128 v[206:209], v180 offset:6144
	ds_read_b128 v[210:213], v180 offset:7168
	global_load_lds_dwordx4 v[174:175], off
	v_lshl_add_u64 v[174:175], s[0:1], 0, v[164:165]
	s_add_i32 m0, s63, 0xe000
	s_nop 0
	global_load_lds_dwordx4 v[174:175], off
	s_waitcnt vmcnt(8)
	s_waitcnt lgkmcnt(0)
	s_barrier
	s_setprio 1
	s_waitcnt lgkmcnt(0)
	v_mfma_f32_16x16x32_bf16 v[142:145], v[10:13], v[182:185], 0
	v_mfma_f32_16x16x32_bf16 v[138:141], v[26:29], v[182:185], 0
	v_mfma_f32_16x16x32_bf16 v[126:129], v[10:13], v[190:193], 0
	v_mfma_f32_16x16x32_bf16 v[122:125], v[26:29], v[190:193], 0
	v_mfma_f32_16x16x32_bf16 v[110:113], v[10:13], v[198:201], 0
	v_mfma_f32_16x16x32_bf16 v[106:109], v[26:29], v[198:201], 0
	v_mfma_f32_16x16x32_bf16 v[94:97], v[10:13], v[206:209], 0
	v_mfma_f32_16x16x32_bf16 v[90:93], v[26:29], v[206:209], 0
	v_mfma_f32_16x16x32_bf16 v[142:145], v[14:17], v[186:189], v[142:145]
	v_mfma_f32_16x16x32_bf16 v[138:141], v[30:33], v[186:189], v[138:141]
	v_mfma_f32_16x16x32_bf16 v[126:129], v[14:17], v[194:197], v[126:129]
	v_mfma_f32_16x16x32_bf16 v[122:125], v[30:33], v[194:197], v[122:125]
	v_mfma_f32_16x16x32_bf16 v[110:113], v[14:17], v[202:205], v[110:113]
	v_mfma_f32_16x16x32_bf16 v[106:109], v[30:33], v[202:205], v[106:109]
	v_mfma_f32_16x16x32_bf16 v[94:97], v[14:17], v[210:213], v[94:97]
	v_mfma_f32_16x16x32_bf16 v[90:93], v[30:33], v[210:213], v[90:93]
	s_setprio 0
	s_setprio 1
	v_mfma_f32_16x16x32_bf16 v[134:137], v[146:149], v[182:185], 0
	v_mfma_f32_16x16x32_bf16 v[130:133], v[166:169], v[182:185], 0
	v_mfma_f32_16x16x32_bf16 v[118:121], v[146:149], v[190:193], 0
	v_mfma_f32_16x16x32_bf16 v[114:117], v[166:169], v[190:193], 0
	v_mfma_f32_16x16x32_bf16 v[102:105], v[146:149], v[198:201], 0
	v_mfma_f32_16x16x32_bf16 v[98:101], v[166:169], v[198:201], 0
	v_mfma_f32_16x16x32_bf16 v[86:89], v[146:149], v[206:209], 0
	v_mfma_f32_16x16x32_bf16 v[82:85], v[166:169], v[206:209], 0
	v_mfma_f32_16x16x32_bf16 v[134:137], v[150:153], v[186:189], v[134:137]
	v_mfma_f32_16x16x32_bf16 v[130:133], v[170:173], v[186:189], v[130:133]
	v_mfma_f32_16x16x32_bf16 v[118:121], v[150:153], v[194:197], v[118:121]
	v_mfma_f32_16x16x32_bf16 v[114:117], v[170:173], v[194:197], v[114:117]
	v_mfma_f32_16x16x32_bf16 v[102:105], v[150:153], v[202:205], v[102:105]
	v_mfma_f32_16x16x32_bf16 v[98:101], v[170:173], v[202:205], v[98:101]
	v_mfma_f32_16x16x32_bf16 v[86:89], v[150:153], v[210:213], v[86:89]
	v_mfma_f32_16x16x32_bf16 v[82:85], v[170:173], v[210:213], v[82:85]
	s_setprio 0
	s_barrier
	s_add_i32 s7, s24, s62
	v_lshl_add_u64 v[174:175], s[40:41], 0, v[158:159]
	s_mov_b32 m0, s7
	ds_read_b128 v[182:185], v180 offset:16384
	ds_read_b128 v[186:189], v180 offset:17408
	ds_read_b128 v[190:193], v180 offset:18432
	ds_read_b128 v[194:197], v180 offset:19456
	ds_read_b128 v[198:201], v180 offset:20480
	ds_read_b128 v[202:205], v180 offset:21504
	ds_read_b128 v[206:209], v180 offset:22528
	ds_read_b128 v[210:213], v180 offset:23552
	global_load_lds_dwordx4 v[174:175], off
	s_add_i32 m0, s7, 0x2000
	s_add_u32 s24, s40, 0x40000
	v_lshl_add_u64 v[214:215], s[40:41], 0, v[154:155]
	s_addc_u32 s25, s41, 0
	s_add_i32 s6, s6, s62
	global_load_lds_dwordx4 v[214:215], off
	v_lshl_add_u64 v[216:217], s[24:25], 0, v[158:159]
	s_mov_b32 m0, s6
	v_lshl_add_u64 v[218:219], s[42:43], 0, v[156:157]
	global_load_lds_dwordx4 v[216:217], off
	v_lshl_add_u64 v[216:217], s[24:25], 0, v[154:155]
	s_add_i32 m0, s6, 0x2000
	s_nop 0
	global_load_lds_dwordx4 v[216:217], off
	v_lshl_add_u64 v[216:217], s[42:43], 0, v[160:161]
	s_mov_b32 m0, s63
	s_nop 0
	global_load_lds_dwordx4 v[216:217], off
	s_mov_b32 m0, s64
	s_nop 0
	global_load_lds_dwordx4 v[218:219], off
	s_waitcnt vmcnt(8)
	s_waitcnt lgkmcnt(0)
	s_barrier
	s_setprio 1
	s_waitcnt lgkmcnt(0)
	v_mfma_f32_16x16x32_bf16 v[78:81], v[10:13], v[182:185], 0
	v_mfma_f32_16x16x32_bf16 v[74:77], v[26:29], v[182:185], 0
	v_mfma_f32_16x16x32_bf16 v[62:65], v[10:13], v[190:193], 0
	v_mfma_f32_16x16x32_bf16 v[58:61], v[26:29], v[190:193], 0
	v_mfma_f32_16x16x32_bf16 v[46:49], v[10:13], v[198:201], 0
	v_mfma_f32_16x16x32_bf16 v[42:45], v[26:29], v[198:201], 0
	v_mfma_f32_16x16x32_bf16 v[10:13], v[10:13], v[206:209], 0
	v_mfma_f32_16x16x32_bf16 v[78:81], v[14:17], v[186:189], v[78:81]
	v_mfma_f32_16x16x32_bf16 v[74:77], v[30:33], v[186:189], v[74:77]
	v_mfma_f32_16x16x32_bf16 v[62:65], v[14:17], v[194:197], v[62:65]
	v_mfma_f32_16x16x32_bf16 v[58:61], v[30:33], v[194:197], v[58:61]
	v_mfma_f32_16x16x32_bf16 v[46:49], v[14:17], v[202:205], v[46:49]
	v_mfma_f32_16x16x32_bf16 v[42:45], v[30:33], v[202:205], v[42:45]
	v_mfma_f32_16x16x32_bf16 v[10:13], v[14:17], v[210:213], v[10:13]
	v_mfma_f32_16x16x32_bf16 v[14:17], v[26:29], v[206:209], 0
	v_mfma_f32_16x16x32_bf16 v[14:17], v[30:33], v[210:213], v[14:17]
	s_setprio 0
	s_setprio 1
	v_mfma_f32_16x16x32_bf16 v[18:21], v[146:149], v[182:185], 0
	v_mfma_f32_16x16x32_bf16 v[26:29], v[150:153], v[186:189], v[18:21]
	v_mfma_f32_16x16x32_bf16 v[18:21], v[166:169], v[182:185], 0
	v_mfma_f32_16x16x32_bf16 v[30:33], v[170:173], v[186:189], v[18:21]
	v_mfma_f32_16x16x32_bf16 v[18:21], v[146:149], v[190:193], 0
	v_mfma_f32_16x16x32_bf16 v[54:57], v[150:153], v[194:197], v[18:21]
	v_mfma_f32_16x16x32_bf16 v[18:21], v[166:169], v[190:193], 0
	v_mfma_f32_16x16x32_bf16 v[50:53], v[170:173], v[194:197], v[18:21]
	v_mfma_f32_16x16x32_bf16 v[18:21], v[146:149], v[198:201], 0
	v_mfma_f32_16x16x32_bf16 v[38:41], v[150:153], v[202:205], v[18:21]
	v_mfma_f32_16x16x32_bf16 v[18:21], v[166:169], v[198:201], 0
	v_mfma_f32_16x16x32_bf16 v[6:9], v[146:149], v[206:209], 0
	v_mfma_f32_16x16x32_bf16 v[2:5], v[166:169], v[206:209], 0
	v_mfma_f32_16x16x32_bf16 v[34:37], v[170:173], v[202:205], v[18:21]
	v_mfma_f32_16x16x32_bf16 v[6:9], v[150:153], v[210:213], v[6:9]
	v_mfma_f32_16x16x32_bf16 v[2:5], v[170:173], v[210:213], v[2:5]
	s_setprio 0
	s_barrier
	s_add_i32 s6, 0, 0x18000
	v_add_u32_e32 v0, s6, v177
	s_add_i32 s7, 0, 0x1c000
	ds_read_b128 v[18:21], v0
	ds_read_b128 v[22:25], v0 offset:1024
	ds_read_b128 v[66:69], v0 offset:2048
	ds_read_b128 v[70:73], v0 offset:3072
	v_add_u32_e32 v0, s7, v177
	ds_read_b128 v[146:149], v0
	ds_read_b128 v[150:153], v0 offset:1024
	ds_read_b128 v[166:169], v0 offset:2048
	ds_read_b128 v[170:173], v0 offset:3072
	s_add_u32 s24, s42, 0x40000
	s_addc_u32 s25, s43, 0
	s_mov_b32 m0, s65
	v_lshl_add_u64 v[220:221], s[24:25], 0, v[160:161]
	ds_read_b128 v[182:185], v180 offset:32768
	ds_read_b128 v[186:189], v180 offset:33792
	ds_read_b128 v[190:193], v180 offset:34816
	ds_read_b128 v[194:197], v180 offset:35840
	ds_read_b128 v[198:201], v180 offset:36864
	ds_read_b128 v[202:205], v180 offset:37888
	ds_read_b128 v[206:209], v180 offset:38912
	ds_read_b128 v[210:213], v180 offset:39936
	global_load_lds_dwordx4 v[220:221], off
	v_lshl_add_u64 v[220:221], s[24:25], 0, v[156:157]
	s_mov_b32 m0, s66
	s_nop 0
	global_load_lds_dwordx4 v[220:221], off
	s_waitcnt vmcnt(8)
	s_waitcnt lgkmcnt(0)
	s_barrier
	s_setprio 1
	s_waitcnt lgkmcnt(0)
	v_mfma_f32_16x16x32_bf16 v[142:145], v[18:21], v[182:185], v[142:145]
	v_mfma_f32_16x16x32_bf16 v[138:141], v[66:69], v[182:185], v[138:141]
	v_mfma_f32_16x16x32_bf16 v[126:129], v[18:21], v[190:193], v[126:129]
	v_mfma_f32_16x16x32_bf16 v[122:125], v[66:69], v[190:193], v[122:125]
	v_mfma_f32_16x16x32_bf16 v[110:113], v[18:21], v[198:201], v[110:113]
	v_mfma_f32_16x16x32_bf16 v[106:109], v[66:69], v[198:201], v[106:109]
	v_mfma_f32_16x16x32_bf16 v[94:97], v[18:21], v[206:209], v[94:97]
	v_mfma_f32_16x16x32_bf16 v[90:93], v[66:69], v[206:209], v[90:93]
	v_mfma_f32_16x16x32_bf16 v[142:145], v[22:25], v[186:189], v[142:145]
	v_mfma_f32_16x16x32_bf16 v[138:141], v[70:73], v[186:189], v[138:141]
	v_mfma_f32_16x16x32_bf16 v[126:129], v[22:25], v[194:197], v[126:129]
	v_mfma_f32_16x16x32_bf16 v[122:125], v[70:73], v[194:197], v[122:125]
	v_mfma_f32_16x16x32_bf16 v[110:113], v[22:25], v[202:205], v[110:113]
	v_mfma_f32_16x16x32_bf16 v[106:109], v[70:73], v[202:205], v[106:109]
	v_mfma_f32_16x16x32_bf16 v[94:97], v[22:25], v[210:213], v[94:97]
	v_mfma_f32_16x16x32_bf16 v[90:93], v[70:73], v[210:213], v[90:93]
	s_setprio 0
	s_setprio 1
	v_mfma_f32_16x16x32_bf16 v[134:137], v[146:149], v[182:185], v[134:137]
	v_mfma_f32_16x16x32_bf16 v[130:133], v[166:169], v[182:185], v[130:133]
	v_mfma_f32_16x16x32_bf16 v[118:121], v[146:149], v[190:193], v[118:121]
	v_mfma_f32_16x16x32_bf16 v[114:117], v[166:169], v[190:193], v[114:117]
	v_mfma_f32_16x16x32_bf16 v[102:105], v[146:149], v[198:201], v[102:105]
	v_mfma_f32_16x16x32_bf16 v[98:101], v[166:169], v[198:201], v[98:101]
	v_mfma_f32_16x16x32_bf16 v[86:89], v[146:149], v[206:209], v[86:89]
	v_mfma_f32_16x16x32_bf16 v[82:85], v[166:169], v[206:209], v[82:85]
	v_mfma_f32_16x16x32_bf16 v[134:137], v[150:153], v[186:189], v[134:137]
	v_mfma_f32_16x16x32_bf16 v[130:133], v[170:173], v[186:189], v[130:133]
	v_mfma_f32_16x16x32_bf16 v[118:121], v[150:153], v[194:197], v[118:121]
	v_mfma_f32_16x16x32_bf16 v[114:117], v[170:173], v[194:197], v[114:117]
	v_mfma_f32_16x16x32_bf16 v[102:105], v[150:153], v[202:205], v[102:105]
	v_mfma_f32_16x16x32_bf16 v[98:101], v[170:173], v[202:205], v[98:101]
	v_mfma_f32_16x16x32_bf16 v[86:89], v[150:153], v[210:213], v[86:89]
	v_mfma_f32_16x16x32_bf16 v[82:85], v[170:173], v[210:213], v[82:85]
	s_setprio 0
	s_barrier
	s_add_i32 s6, s6, s62
	v_lshl_add_u64 v[174:175], v[174:175], 0, s[84:85]
	s_mov_b32 m0, s6
	ds_read_b128 v[182:185], v180 offset:49152
	ds_read_b128 v[186:189], v180 offset:50176
	ds_read_b128 v[190:193], v180 offset:51200
	ds_read_b128 v[194:197], v180 offset:52224
	ds_read_b128 v[198:201], v180 offset:53248
	ds_read_b128 v[202:205], v180 offset:54272
	ds_read_b128 v[206:209], v180 offset:55296
	ds_read_b128 v[210:213], v180 offset:56320
	global_load_lds_dwordx4 v[174:175], off
	s_add_i32 m0, s6, 0x2000
	s_add_u32 s24, s40, 0x40080
	v_lshl_add_u64 v[174:175], v[214:215], 0, s[84:85]
	s_addc_u32 s25, s41, 0
	s_add_i32 s6, s7, s62
	global_load_lds_dwordx4 v[174:175], off
	v_lshl_add_u64 v[174:175], s[24:25], 0, v[158:159]
	s_mov_b32 m0, s6
	s_nop 0
	global_load_lds_dwordx4 v[174:175], off
	v_lshl_add_u64 v[174:175], s[24:25], 0, v[154:155]
	s_add_i32 m0, s6, 0x2000
	s_nop 0
	global_load_lds_dwordx4 v[174:175], off
	v_lshl_add_u64 v[174:175], v[216:217], 0, s[84:85]
	s_mov_b32 m0, s8
	s_nop 0
	global_load_lds_dwordx4 v[174:175], off
	v_lshl_add_u64 v[174:175], v[218:219], 0, s[84:85]
	s_mov_b32 m0, s67
	s_nop 0
	global_load_lds_dwordx4 v[174:175], off
	s_waitcnt vmcnt(8)
	s_waitcnt lgkmcnt(0)
	s_barrier
	s_setprio 1
	s_waitcnt lgkmcnt(0)
	v_mfma_f32_16x16x32_bf16 v[78:81], v[18:21], v[182:185], v[78:81]
	v_mfma_f32_16x16x32_bf16 v[62:65], v[18:21], v[190:193], v[62:65]
	v_mfma_f32_16x16x32_bf16 v[46:49], v[18:21], v[198:201], v[46:49]
	v_mfma_f32_16x16x32_bf16 v[10:13], v[18:21], v[206:209], v[10:13]
	v_mfma_f32_16x16x32_bf16 v[78:81], v[22:25], v[186:189], v[78:81]
	v_mfma_f32_16x16x32_bf16 v[74:77], v[66:69], v[182:185], v[74:77]
	v_mfma_f32_16x16x32_bf16 v[62:65], v[22:25], v[194:197], v[62:65]
	v_mfma_f32_16x16x32_bf16 v[58:61], v[66:69], v[190:193], v[58:61]
	v_mfma_f32_16x16x32_bf16 v[46:49], v[22:25], v[202:205], v[46:49]
	v_mfma_f32_16x16x32_bf16 v[42:45], v[66:69], v[198:201], v[42:45]
	v_mfma_f32_16x16x32_bf16 v[22:25], v[22:25], v[210:213], v[10:13]
	v_mfma_f32_16x16x32_bf16 v[10:13], v[66:69], v[206:209], v[14:17]
	v_mfma_f32_16x16x32_bf16 v[74:77], v[70:73], v[186:189], v[74:77]
	v_mfma_f32_16x16x32_bf16 v[58:61], v[70:73], v[194:197], v[58:61]
	v_mfma_f32_16x16x32_bf16 v[42:45], v[70:73], v[202:205], v[42:45]
	v_mfma_f32_16x16x32_bf16 v[18:21], v[70:73], v[210:213], v[10:13]
	s_setprio 0
	s_setprio 1
	v_mfma_f32_16x16x32_bf16 v[10:13], v[146:149], v[182:185], v[26:29]
	v_mfma_f32_16x16x32_bf16 v[70:73], v[150:153], v[186:189], v[10:13]
	v_mfma_f32_16x16x32_bf16 v[10:13], v[166:169], v[182:185], v[30:33]
	v_mfma_f32_16x16x32_bf16 v[66:69], v[170:173], v[186:189], v[10:13]
	v_mfma_f32_16x16x32_bf16 v[10:13], v[146:149], v[190:193], v[54:57]
	v_mfma_f32_16x16x32_bf16 v[54:57], v[150:153], v[194:197], v[10:13]
	v_mfma_f32_16x16x32_bf16 v[10:13], v[166:169], v[190:193], v[50:53]
	v_mfma_f32_16x16x32_bf16 v[50:53], v[170:173], v[194:197], v[10:13]
	v_mfma_f32_16x16x32_bf16 v[10:13], v[146:149], v[198:201], v[38:41]
	v_mfma_f32_16x16x32_bf16 v[38:41], v[150:153], v[202:205], v[10:13]
	v_mfma_f32_16x16x32_bf16 v[10:13], v[166:169], v[198:201], v[34:37]
	v_mfma_f32_16x16x32_bf16 v[6:9], v[146:149], v[206:209], v[6:9]
	v_mfma_f32_16x16x32_bf16 v[2:5], v[166:169], v[206:209], v[2:5]
	v_mfma_f32_16x16x32_bf16 v[34:37], v[170:173], v[202:205], v[10:13]
	v_mfma_f32_16x16x32_bf16 v[6:9], v[150:153], v[210:213], v[6:9]
	v_mfma_f32_16x16x32_bf16 v[2:5], v[170:173], v[210:213], v[2:5]
	s_setprio 0
	s_barrier
	s_add_i32 s71, s71, 2
	s_add_u32 s0, s0, 0x100
	s_addc_u32 s1, s1, 0
	s_add_u32 s59, s59, 0x100
	s_addc_u32 s70, s70, 0
	s_cmp_gt_u32 s71, 13

.LBB0_559:
	s_ashr_i32 s47, s46, 31
	s_lshl_b64 s[24:25], s[46:47], 19
	s_add_u32 s48, s92, s24
	s_addc_u32 s49, s93, s25
	s_and_b64 s[24:25], s[38:39], exec
	s_cselect_b32 s47, s49, s41
	s_cselect_b32 s62, s48, s40
	s_ashr_i32 s45, s44, 31
	s_lshl_b64 s[24:25], s[44:45], 19
	s_add_u32 s50, s8, s24
	s_addc_u32 s51, s35, s25
	s_and_b64 s[24:25], s[38:39], exec
	s_cselect_b32 s45, s51, s43
	s_cselect_b32 s63, s50, s42
	s_add_u32 s40, s40, 0x40080
	s_addc_u32 s41, s41, 0
	s_add_u32 s64, s42, 0x100
	s_addc_u32 s65, s43, 0
	s_mov_b32 s66, -2
	s_add_u32 s6, s40, 0xfffc0080
	s_addc_u32 s7, s41, -1
	s_add_i32 s24, 0, 0x10000
	s_cmp_eq_u32 s66, 12
	s_cselect_b32 s53, s47, s7
	s_cselect_b32 s52, s62, s6
	v_add_u32_e32 v0, s24, v193
	s_cselect_b32 s43, s45, s65
	s_cselect_b32 s42, s63, s64
	s_add_i32 s6, 0, 0x14000
	ds_read_b128 v[74:77], v0
	ds_read_b128 v[86:89], v0 offset:1024
	ds_read_b128 v[98:101], v0 offset:2048
	ds_read_b128 v[102:105], v0 offset:3072
	v_add_u32_e32 v0, s6, v193
	ds_read_b128 v[118:121], v0
	ds_read_b128 v[126:129], v0 offset:1024
	ds_read_b128 v[138:141], v0 offset:2048
	ds_read_b128 v[142:145], v0 offset:3072
	v_lshl_add_u64 v[188:189], s[40:41], 0, v[180:181]
	s_add_i32 m0, s55, 0xc000
	ds_read_b128 v[154:157], v213
	ds_read_b128 v[162:165], v213 offset:1024
	ds_read_b128 v[184:187], v213 offset:2048
	ds_read_b128 v[194:197], v213 offset:3072
	ds_read_b128 v[198:201], v213 offset:4096
	ds_read_b128 v[214:217], v213 offset:5120
	ds_read_b128 v[218:221], v213 offset:6144
	ds_read_b128 v[222:225], v213 offset:7168
	global_load_lds_dwordx4 v[188:189], off
	v_lshl_add_u64 v[188:189], s[40:41], 0, v[182:183]
	s_add_i32 m0, s55, 0xe000
	s_nop 0
	global_load_lds_dwordx4 v[188:189], off
	s_waitcnt vmcnt(8)
	s_waitcnt lgkmcnt(0)
	s_barrier
	s_setprio 1
	s_waitcnt lgkmcnt(0)
	v_mfma_f32_16x16x32_bf16 v[166:169], v[74:77], v[154:157], 0
	v_mfma_f32_16x16x32_bf16 v[158:161], v[98:101], v[154:157], 0
	v_mfma_f32_16x16x32_bf16 v[134:137], v[74:77], v[184:187], 0
	v_mfma_f32_16x16x32_bf16 v[130:133], v[98:101], v[184:187], 0
	v_mfma_f32_16x16x32_bf16 v[110:113], v[74:77], v[198:201], 0
	v_mfma_f32_16x16x32_bf16 v[106:109], v[98:101], v[198:201], 0
	v_mfma_f32_16x16x32_bf16 v[82:85], v[74:77], v[218:221], 0
	v_mfma_f32_16x16x32_bf16 v[78:81], v[98:101], v[218:221], 0
	v_mfma_f32_16x16x32_bf16 v[166:169], v[86:89], v[162:165], v[166:169]
	v_mfma_f32_16x16x32_bf16 v[158:161], v[102:105], v[162:165], v[158:161]
	v_mfma_f32_16x16x32_bf16 v[134:137], v[86:89], v[194:197], v[134:137]
	v_mfma_f32_16x16x32_bf16 v[130:133], v[102:105], v[194:197], v[130:133]
	v_mfma_f32_16x16x32_bf16 v[110:113], v[86:89], v[214:217], v[110:113]
	v_mfma_f32_16x16x32_bf16 v[106:109], v[102:105], v[214:217], v[106:109]
	v_mfma_f32_16x16x32_bf16 v[82:85], v[86:89], v[222:225], v[82:85]
	v_mfma_f32_16x16x32_bf16 v[78:81], v[102:105], v[222:225], v[78:81]
	s_setprio 0
	s_setprio 1
	v_mfma_f32_16x16x32_bf16 v[150:153], v[118:121], v[154:157], 0
	v_mfma_f32_16x16x32_bf16 v[146:149], v[138:141], v[154:157], 0
	v_mfma_f32_16x16x32_bf16 v[122:125], v[118:121], v[184:187], 0
	v_mfma_f32_16x16x32_bf16 v[114:117], v[138:141], v[184:187], 0
	v_mfma_f32_16x16x32_bf16 v[94:97], v[118:121], v[198:201], 0
	v_mfma_f32_16x16x32_bf16 v[90:93], v[138:141], v[198:201], 0
	v_mfma_f32_16x16x32_bf16 v[70:73], v[118:121], v[218:221], 0
	v_mfma_f32_16x16x32_bf16 v[66:69], v[138:141], v[218:221], 0
	v_mfma_f32_16x16x32_bf16 v[150:153], v[126:129], v[162:165], v[150:153]
	v_mfma_f32_16x16x32_bf16 v[146:149], v[142:145], v[162:165], v[146:149]
	v_mfma_f32_16x16x32_bf16 v[122:125], v[126:129], v[194:197], v[122:125]
	v_mfma_f32_16x16x32_bf16 v[114:117], v[142:145], v[194:197], v[114:117]
	v_mfma_f32_16x16x32_bf16 v[94:97], v[126:129], v[214:217], v[94:97]
	v_mfma_f32_16x16x32_bf16 v[90:93], v[142:145], v[214:217], v[90:93]
	v_mfma_f32_16x16x32_bf16 v[70:73], v[126:129], v[222:225], v[70:73]
	v_mfma_f32_16x16x32_bf16 v[66:69], v[142:145], v[222:225], v[66:69]
	s_setprio 0
	s_barrier
	s_add_i32 s7, s24, s54
	v_lshl_add_u64 v[188:189], s[42:43], 0, v[174:175]
	s_mov_b32 m0, s7
	ds_read_b128 v[154:157], v213 offset:16384
	ds_read_b128 v[162:165], v213 offset:17408
	ds_read_b128 v[184:187], v213 offset:18432
	ds_read_b128 v[194:197], v213 offset:19456
	ds_read_b128 v[198:201], v213 offset:20480
	ds_read_b128 v[214:217], v213 offset:21504
	ds_read_b128 v[218:221], v213 offset:22528
	ds_read_b128 v[222:225], v213 offset:23552
	global_load_lds_dwordx4 v[188:189], off
	s_add_i32 m0, s7, 0x2000
	s_add_u32 s24, s42, 0x40000
	v_lshl_add_u64 v[202:203], s[42:43], 0, v[170:171]
	s_addc_u32 s25, s43, 0
	s_add_i32 s6, s6, s54
	global_load_lds_dwordx4 v[202:203], off
	v_lshl_add_u64 v[226:227], s[24:25], 0, v[174:175]
	s_mov_b32 m0, s6
	v_lshl_add_u64 v[230:231], s[52:53], 0, v[172:173]
	global_load_lds_dwordx4 v[226:227], off
	v_lshl_add_u64 v[226:227], s[24:25], 0, v[170:171]
	s_add_i32 m0, s6, 0x2000
	s_nop 0
	global_load_lds_dwordx4 v[226:227], off
	v_lshl_add_u64 v[226:227], s[52:53], 0, v[176:177]
	s_mov_b32 m0, s55
	s_nop 0
	global_load_lds_dwordx4 v[226:227], off
	s_mov_b32 m0, s56
	s_nop 0
	global_load_lds_dwordx4 v[230:231], off
	s_waitcnt vmcnt(8)
	s_waitcnt lgkmcnt(0)
	s_barrier
	s_setprio 1
	s_waitcnt lgkmcnt(0)
	v_mfma_f32_16x16x32_bf16 v[62:65], v[74:77], v[154:157], 0
	v_mfma_f32_16x16x32_bf16 v[58:61], v[98:101], v[154:157], 0
	v_mfma_f32_16x16x32_bf16 v[46:49], v[74:77], v[184:187], 0
	v_mfma_f32_16x16x32_bf16 v[42:45], v[98:101], v[184:187], 0
	v_mfma_f32_16x16x32_bf16 v[30:33], v[74:77], v[198:201], 0
	v_mfma_f32_16x16x32_bf16 v[26:29], v[98:101], v[198:201], 0
	v_mfma_f32_16x16x32_bf16 v[14:17], v[74:77], v[218:221], 0
	v_mfma_f32_16x16x32_bf16 v[10:13], v[98:101], v[218:221], 0
	v_mfma_f32_16x16x32_bf16 v[62:65], v[86:89], v[162:165], v[62:65]
	v_mfma_f32_16x16x32_bf16 v[58:61], v[102:105], v[162:165], v[58:61]
	v_mfma_f32_16x16x32_bf16 v[46:49], v[86:89], v[194:197], v[46:49]
	v_mfma_f32_16x16x32_bf16 v[42:45], v[102:105], v[194:197], v[42:45]
	v_mfma_f32_16x16x32_bf16 v[30:33], v[86:89], v[214:217], v[30:33]
	v_mfma_f32_16x16x32_bf16 v[26:29], v[102:105], v[214:217], v[26:29]
	v_mfma_f32_16x16x32_bf16 v[14:17], v[86:89], v[222:225], v[14:17]
	v_mfma_f32_16x16x32_bf16 v[10:13], v[102:105], v[222:225], v[10:13]
	s_setprio 0
	s_setprio 1
	v_mfma_f32_16x16x32_bf16 v[54:57], v[118:121], v[154:157], 0
	v_mfma_f32_16x16x32_bf16 v[50:53], v[138:141], v[154:157], 0
	v_mfma_f32_16x16x32_bf16 v[38:41], v[118:121], v[184:187], 0
	v_mfma_f32_16x16x32_bf16 v[34:37], v[138:141], v[184:187], 0
	v_mfma_f32_16x16x32_bf16 v[22:25], v[118:121], v[198:201], 0
	v_mfma_f32_16x16x32_bf16 v[18:21], v[138:141], v[198:201], 0
	v_mfma_f32_16x16x32_bf16 v[6:9], v[118:121], v[218:221], 0
	v_mfma_f32_16x16x32_bf16 v[2:5], v[138:141], v[218:221], 0
	v_mfma_f32_16x16x32_bf16 v[54:57], v[126:129], v[162:165], v[54:57]
	v_mfma_f32_16x16x32_bf16 v[50:53], v[142:145], v[162:165], v[50:53]
	v_mfma_f32_16x16x32_bf16 v[38:41], v[126:129], v[194:197], v[38:41]
	v_mfma_f32_16x16x32_bf16 v[34:37], v[142:145], v[194:197], v[34:37]
	v_mfma_f32_16x16x32_bf16 v[22:25], v[126:129], v[214:217], v[22:25]
	v_mfma_f32_16x16x32_bf16 v[18:21], v[142:145], v[214:217], v[18:21]
	v_mfma_f32_16x16x32_bf16 v[6:9], v[126:129], v[222:225], v[6:9]
	v_mfma_f32_16x16x32_bf16 v[2:5], v[142:145], v[222:225], v[2:5]
	s_setprio 0
	s_barrier
	s_add_i32 s6, 0, 0x18000
	v_add_u32_e32 v0, s6, v193
	s_add_i32 s7, 0, 0x1c000
	ds_read_b128 v[74:77], v0
	ds_read_b128 v[86:89], v0 offset:1024
	ds_read_b128 v[98:101], v0 offset:2048
	ds_read_b128 v[102:105], v0 offset:3072
	v_add_u32_e32 v0, s7, v193
	ds_read_b128 v[118:121], v0
	ds_read_b128 v[126:129], v0 offset:1024
	ds_read_b128 v[138:141], v0 offset:2048
	ds_read_b128 v[142:145], v0 offset:3072
	s_add_u32 s24, s52, 0x40000
	s_addc_u32 s25, s53, 0
	s_mov_b32 m0, s57
	v_lshl_add_u64 v[232:233], s[24:25], 0, v[176:177]
	ds_read_b128 v[154:157], v213 offset:32768
	ds_read_b128 v[162:165], v213 offset:33792
	ds_read_b128 v[184:187], v213 offset:34816
	ds_read_b128 v[194:197], v213 offset:35840
	ds_read_b128 v[198:201], v213 offset:36864
	ds_read_b128 v[214:217], v213 offset:37888
	ds_read_b128 v[218:221], v213 offset:38912
	ds_read_b128 v[222:225], v213 offset:39936
	global_load_lds_dwordx4 v[232:233], off
	v_lshl_add_u64 v[232:233], s[24:25], 0, v[172:173]
	s_mov_b32 m0, s58
	s_nop 0
	global_load_lds_dwordx4 v[232:233], off
	s_waitcnt vmcnt(8)
	s_waitcnt lgkmcnt(0)
	s_barrier
	s_setprio 1
	s_waitcnt lgkmcnt(0)
	v_mfma_f32_16x16x32_bf16 v[166:169], v[74:77], v[154:157], v[166:169]
	v_mfma_f32_16x16x32_bf16 v[158:161], v[98:101], v[154:157], v[158:161]
	v_mfma_f32_16x16x32_bf16 v[134:137], v[74:77], v[184:187], v[134:137]
	v_mfma_f32_16x16x32_bf16 v[130:133], v[98:101], v[184:187], v[130:133]
	v_mfma_f32_16x16x32_bf16 v[110:113], v[74:77], v[198:201], v[110:113]
	v_mfma_f32_16x16x32_bf16 v[106:109], v[98:101], v[198:201], v[106:109]
	v_mfma_f32_16x16x32_bf16 v[82:85], v[74:77], v[218:221], v[82:85]
	v_mfma_f32_16x16x32_bf16 v[78:81], v[98:101], v[218:221], v[78:81]
	v_mfma_f32_16x16x32_bf16 v[166:169], v[86:89], v[162:165], v[166:169]
	v_mfma_f32_16x16x32_bf16 v[158:161], v[102:105], v[162:165], v[158:161]
	v_mfma_f32_16x16x32_bf16 v[134:137], v[86:89], v[194:197], v[134:137]
	v_mfma_f32_16x16x32_bf16 v[130:133], v[102:105], v[194:197], v[130:133]
	v_mfma_f32_16x16x32_bf16 v[110:113], v[86:89], v[214:217], v[110:113]
	v_mfma_f32_16x16x32_bf16 v[106:109], v[102:105], v[214:217], v[106:109]
	v_mfma_f32_16x16x32_bf16 v[82:85], v[86:89], v[222:225], v[82:85]
	v_mfma_f32_16x16x32_bf16 v[78:81], v[102:105], v[222:225], v[78:81]
	s_setprio 0
	s_setprio 1
	v_mfma_f32_16x16x32_bf16 v[150:153], v[118:121], v[154:157], v[150:153]
	v_mfma_f32_16x16x32_bf16 v[146:149], v[138:141], v[154:157], v[146:149]
	v_mfma_f32_16x16x32_bf16 v[122:125], v[118:121], v[184:187], v[122:125]
	v_mfma_f32_16x16x32_bf16 v[114:117], v[138:141], v[184:187], v[114:117]
	v_mfma_f32_16x16x32_bf16 v[94:97], v[118:121], v[198:201], v[94:97]
	v_mfma_f32_16x16x32_bf16 v[90:93], v[138:141], v[198:201], v[90:93]
	v_mfma_f32_16x16x32_bf16 v[70:73], v[118:121], v[218:221], v[70:73]
	v_mfma_f32_16x16x32_bf16 v[66:69], v[138:141], v[218:221], v[66:69]
	v_mfma_f32_16x16x32_bf16 v[150:153], v[126:129], v[162:165], v[150:153]
	v_mfma_f32_16x16x32_bf16 v[146:149], v[142:145], v[162:165], v[146:149]
	v_mfma_f32_16x16x32_bf16 v[122:125], v[126:129], v[194:197], v[122:125]
	v_mfma_f32_16x16x32_bf16 v[114:117], v[142:145], v[194:197], v[114:117]
	v_mfma_f32_16x16x32_bf16 v[94:97], v[126:129], v[214:217], v[94:97]
	v_mfma_f32_16x16x32_bf16 v[90:93], v[142:145], v[214:217], v[90:93]
	v_mfma_f32_16x16x32_bf16 v[70:73], v[126:129], v[222:225], v[70:73]
	v_mfma_f32_16x16x32_bf16 v[66:69], v[142:145], v[222:225], v[66:69]
	s_setprio 0
	s_barrier
	s_add_i32 s6, s6, s54
	v_lshl_add_u64 v[188:189], v[188:189], 0, s[84:85]
	s_mov_b32 m0, s6
	ds_read_b128 v[154:157], v213 offset:49152
	ds_read_b128 v[162:165], v213 offset:50176
	ds_read_b128 v[184:187], v213 offset:51200
	ds_read_b128 v[194:197], v213 offset:52224
	ds_read_b128 v[198:201], v213 offset:53248
	ds_read_b128 v[214:217], v213 offset:54272
	ds_read_b128 v[218:221], v213 offset:55296
	ds_read_b128 v[222:225], v213 offset:56320
	global_load_lds_dwordx4 v[188:189], off
	s_add_i32 m0, s6, 0x2000
	s_add_u32 s24, s42, 0x40080
	v_lshl_add_u64 v[188:189], v[202:203], 0, s[84:85]
	s_addc_u32 s25, s43, 0
	s_add_i32 s6, s7, s54
	global_load_lds_dwordx4 v[188:189], off
	v_lshl_add_u64 v[188:189], s[24:25], 0, v[174:175]
	s_mov_b32 m0, s6
	s_nop 0
	global_load_lds_dwordx4 v[188:189], off
	v_lshl_add_u64 v[188:189], s[24:25], 0, v[170:171]
	s_add_i32 m0, s6, 0x2000
	s_nop 0
	global_load_lds_dwordx4 v[188:189], off
	v_lshl_add_u64 v[188:189], v[226:227], 0, s[84:85]
	s_mov_b32 m0, s59
	s_nop 0
	global_load_lds_dwordx4 v[188:189], off
	v_lshl_add_u64 v[188:189], v[230:231], 0, s[84:85]
	s_mov_b32 m0, s60
	s_nop 0
	global_load_lds_dwordx4 v[188:189], off
	s_waitcnt vmcnt(8)
	s_waitcnt lgkmcnt(0)
	s_barrier
	s_setprio 1
	s_waitcnt lgkmcnt(0)
	v_mfma_f32_16x16x32_bf16 v[62:65], v[74:77], v[154:157], v[62:65]
	v_mfma_f32_16x16x32_bf16 v[58:61], v[98:101], v[154:157], v[58:61]
	v_mfma_f32_16x16x32_bf16 v[46:49], v[74:77], v[184:187], v[46:49]
	v_mfma_f32_16x16x32_bf16 v[42:45], v[98:101], v[184:187], v[42:45]
	v_mfma_f32_16x16x32_bf16 v[30:33], v[74:77], v[198:201], v[30:33]
	v_mfma_f32_16x16x32_bf16 v[26:29], v[98:101], v[198:201], v[26:29]
	v_mfma_f32_16x16x32_bf16 v[14:17], v[74:77], v[218:221], v[14:17]
	v_mfma_f32_16x16x32_bf16 v[10:13], v[98:101], v[218:221], v[10:13]
	v_mfma_f32_16x16x32_bf16 v[62:65], v[86:89], v[162:165], v[62:65]
	v_mfma_f32_16x16x32_bf16 v[58:61], v[102:105], v[162:165], v[58:61]
	v_mfma_f32_16x16x32_bf16 v[46:49], v[86:89], v[194:197], v[46:49]
	v_mfma_f32_16x16x32_bf16 v[42:45], v[102:105], v[194:197], v[42:45]
	v_mfma_f32_16x16x32_bf16 v[30:33], v[86:89], v[214:217], v[30:33]
	v_mfma_f32_16x16x32_bf16 v[26:29], v[102:105], v[214:217], v[26:29]
	v_mfma_f32_16x16x32_bf16 v[14:17], v[86:89], v[222:225], v[14:17]
	v_mfma_f32_16x16x32_bf16 v[10:13], v[102:105], v[222:225], v[10:13]
	s_setprio 0
	s_setprio 1
	v_mfma_f32_16x16x32_bf16 v[54:57], v[118:121], v[154:157], v[54:57]
	v_mfma_f32_16x16x32_bf16 v[50:53], v[138:141], v[154:157], v[50:53]
	v_mfma_f32_16x16x32_bf16 v[38:41], v[118:121], v[184:187], v[38:41]
	v_mfma_f32_16x16x32_bf16 v[34:37], v[138:141], v[184:187], v[34:37]
	v_mfma_f32_16x16x32_bf16 v[22:25], v[118:121], v[198:201], v[22:25]
	v_mfma_f32_16x16x32_bf16 v[18:21], v[138:141], v[198:201], v[18:21]
	v_mfma_f32_16x16x32_bf16 v[6:9], v[118:121], v[218:221], v[6:9]
	v_mfma_f32_16x16x32_bf16 v[2:5], v[138:141], v[218:221], v[2:5]
	v_mfma_f32_16x16x32_bf16 v[54:57], v[126:129], v[162:165], v[54:57]
	v_mfma_f32_16x16x32_bf16 v[50:53], v[142:145], v[162:165], v[50:53]
	v_mfma_f32_16x16x32_bf16 v[38:41], v[126:129], v[194:197], v[38:41]
	v_mfma_f32_16x16x32_bf16 v[34:37], v[142:145], v[194:197], v[34:37]
	v_mfma_f32_16x16x32_bf16 v[22:25], v[126:129], v[214:217], v[22:25]
	v_mfma_f32_16x16x32_bf16 v[18:21], v[142:145], v[214:217], v[18:21]
	v_mfma_f32_16x16x32_bf16 v[6:9], v[126:129], v[222:225], v[6:9]
	v_mfma_f32_16x16x32_bf16 v[2:5], v[142:145], v[222:225], v[2:5]
	s_setprio 0
	s_barrier
	s_add_i32 s66, s66, 2
	s_add_u32 s40, s40, 0x100
	s_addc_u32 s41, s41, 0
	s_add_u32 s64, s64, 0x100
	s_addc_u32 s65, s65, 0
	s_cmp_gt_u32 s66, 13

.LBB0_762:
	s_add_u32 s50, s50, 0x80
	s_addc_u32 s51, s51, 0
	s_add_u32 s37, s52, 0x100
	s_addc_u32 s54, s53, 0
	s_mov_b32 s24, 0
	s_waitcnt lgkmcnt(0)
	s_waitcnt vmcnt(0)
	s_add_i32 s25, s24, 2
	s_add_u32 s6, s50, 0x80
	s_addc_u32 s7, s51, 0
	s_add_i32 s55, 0, 0x10000
	s_cmp_eq_u32 s67, s24
	s_cselect_b32 s53, s41, s7
	s_cselect_b32 s52, s40, s6
	s_cselect_b32 s7, s49, s54
	s_cselect_b32 s6, s48, s37
	s_add_i32 s24, 0, 0x14000
	v_add_u32_e32 v142, s55, v188
	v_add_u32_e32 v171, s24, v188
	ds_read_b128 v[122:125], v142
	ds_read_b128 v[134:137], v142 offset:1024
	ds_read_b128 v[138:141], v142 offset:2048
	ds_read_b128 v[142:145], v142 offset:3072
	ds_read_b128 v[146:149], v171
	ds_read_b128 v[150:153], v171 offset:1024
	ds_read_b128 v[154:157], v171 offset:2048
	ds_read_b128 v[172:175], v171 offset:3072
	v_lshl_add_u64 v[184:185], s[50:51], 0, v[166:167]
	s_add_i32 m0, s57, 0xc000
	ds_read_b128 v[176:179], v190
	ds_read_b128 v[180:183], v190 offset:1024
	ds_read_b128 v[192:195], v190 offset:2048
	ds_read_b128 v[196:199], v190 offset:3072
	ds_read_b128 v[200:203], v190 offset:4096
	ds_read_b128 v[204:207], v190 offset:5120
	ds_read_b128 v[208:211], v190 offset:6144
	ds_read_b128 v[212:215], v190 offset:7168
	global_load_lds_dwordx4 v[184:185], off
	v_lshl_add_u64 v[184:185], s[50:51], 0, v[168:169]
	s_add_i32 m0, s57, 0xe000
	s_nop 0
	global_load_lds_dwordx4 v[184:185], off
	s_waitcnt vmcnt(8)
	s_waitcnt lgkmcnt(0)
	s_barrier
	s_setprio 1
	s_waitcnt lgkmcnt(0)
	v_mfma_f32_16x16x32_bf16 v[130:133], v[122:125], v[176:179], 0
	v_mfma_f32_16x16x32_bf16 v[126:129], v[138:141], v[176:179], 0
	v_mfma_f32_16x16x32_bf16 v[110:113], v[122:125], v[192:195], 0
	v_mfma_f32_16x16x32_bf16 v[106:109], v[138:141], v[192:195], 0
	v_mfma_f32_16x16x32_bf16 v[94:97], v[122:125], v[200:203], 0
	v_mfma_f32_16x16x32_bf16 v[90:93], v[138:141], v[200:203], 0
	v_mfma_f32_16x16x32_bf16 v[78:81], v[122:125], v[208:211], 0
	v_mfma_f32_16x16x32_bf16 v[74:77], v[138:141], v[208:211], 0
	v_mfma_f32_16x16x32_bf16 v[130:133], v[134:137], v[180:183], v[130:133]
	v_mfma_f32_16x16x32_bf16 v[126:129], v[142:145], v[180:183], v[126:129]
	v_mfma_f32_16x16x32_bf16 v[110:113], v[134:137], v[196:199], v[110:113]
	v_mfma_f32_16x16x32_bf16 v[106:109], v[142:145], v[196:199], v[106:109]
	v_mfma_f32_16x16x32_bf16 v[94:97], v[134:137], v[204:207], v[94:97]
	v_mfma_f32_16x16x32_bf16 v[90:93], v[142:145], v[204:207], v[90:93]
	v_mfma_f32_16x16x32_bf16 v[78:81], v[134:137], v[212:215], v[78:81]
	v_mfma_f32_16x16x32_bf16 v[74:77], v[142:145], v[212:215], v[74:77]
	s_setprio 0
	s_setprio 1
	v_mfma_f32_16x16x32_bf16 v[118:121], v[146:149], v[176:179], 0
	v_mfma_f32_16x16x32_bf16 v[114:117], v[154:157], v[176:179], 0
	v_mfma_f32_16x16x32_bf16 v[102:105], v[146:149], v[192:195], 0
	v_mfma_f32_16x16x32_bf16 v[98:101], v[154:157], v[192:195], 0
	v_mfma_f32_16x16x32_bf16 v[86:89], v[146:149], v[200:203], 0
	v_mfma_f32_16x16x32_bf16 v[82:85], v[154:157], v[200:203], 0
	v_mfma_f32_16x16x32_bf16 v[70:73], v[146:149], v[208:211], 0
	v_mfma_f32_16x16x32_bf16 v[66:69], v[154:157], v[208:211], 0
	v_mfma_f32_16x16x32_bf16 v[118:121], v[150:153], v[180:183], v[118:121]
	v_mfma_f32_16x16x32_bf16 v[114:117], v[172:175], v[180:183], v[114:117]
	v_mfma_f32_16x16x32_bf16 v[102:105], v[150:153], v[196:199], v[102:105]
	v_mfma_f32_16x16x32_bf16 v[98:101], v[172:175], v[196:199], v[98:101]
	v_mfma_f32_16x16x32_bf16 v[86:89], v[150:153], v[204:207], v[86:89]
	v_mfma_f32_16x16x32_bf16 v[82:85], v[172:175], v[204:207], v[82:85]
	v_mfma_f32_16x16x32_bf16 v[70:73], v[150:153], v[212:215], v[70:73]
	v_mfma_f32_16x16x32_bf16 v[66:69], v[172:175], v[212:215], v[66:69]
	s_setprio 0
	s_barrier
	s_add_i32 s55, s55, s56
	v_lshl_add_u64 v[184:185], s[6:7], 0, v[162:163]
	s_mov_b32 m0, s55
	ds_read_b128 v[176:179], v190 offset:16384
	ds_read_b128 v[180:183], v190 offset:17408
	ds_read_b128 v[192:195], v190 offset:18432
	ds_read_b128 v[196:199], v190 offset:19456
	ds_read_b128 v[200:203], v190 offset:20480
	ds_read_b128 v[204:207], v190 offset:21504
	ds_read_b128 v[208:211], v190 offset:22528
	ds_read_b128 v[212:215], v190 offset:23552
	global_load_lds_dwordx4 v[184:185], off
	s_add_i32 m0, s55, 0x2000
	v_lshl_add_u64 v[216:217], s[6:7], 0, v[158:159]
	s_add_u32 s6, s6, s8
	s_addc_u32 s7, s7, 0
	s_add_i32 s24, s24, s56
	global_load_lds_dwordx4 v[216:217], off
	v_lshl_add_u64 v[218:219], s[6:7], 0, v[162:163]
	s_mov_b32 m0, s24
	v_lshl_add_u64 v[220:221], s[6:7], 0, v[158:159]
	global_load_lds_dwordx4 v[218:219], off
	s_add_i32 m0, s24, 0x2000
	v_lshl_add_u64 v[222:223], s[52:53], 0, v[164:165]
	global_load_lds_dwordx4 v[220:221], off
	s_mov_b32 m0, s57
	v_lshl_add_u64 v[224:225], s[52:53], 0, v[160:161]
	global_load_lds_dwordx4 v[222:223], off
	s_mov_b32 m0, s58
	s_nop 0
	global_load_lds_dwordx4 v[224:225], off
	s_waitcnt vmcnt(8)
	s_waitcnt lgkmcnt(0)
	s_barrier
	s_setprio 1
	s_waitcnt lgkmcnt(0)
	v_mfma_f32_16x16x32_bf16 v[62:65], v[122:125], v[176:179], 0
	v_mfma_f32_16x16x32_bf16 v[58:61], v[138:141], v[176:179], 0
	v_mfma_f32_16x16x32_bf16 v[46:49], v[122:125], v[192:195], 0
	v_mfma_f32_16x16x32_bf16 v[42:45], v[138:141], v[192:195], 0
	v_mfma_f32_16x16x32_bf16 v[30:33], v[122:125], v[200:203], 0
	v_mfma_f32_16x16x32_bf16 v[26:29], v[138:141], v[200:203], 0
	v_mfma_f32_16x16x32_bf16 v[14:17], v[122:125], v[208:211], 0
	v_mfma_f32_16x16x32_bf16 v[10:13], v[138:141], v[208:211], 0
	v_mfma_f32_16x16x32_bf16 v[62:65], v[134:137], v[180:183], v[62:65]
	v_mfma_f32_16x16x32_bf16 v[58:61], v[142:145], v[180:183], v[58:61]
	v_mfma_f32_16x16x32_bf16 v[46:49], v[134:137], v[196:199], v[46:49]
	v_mfma_f32_16x16x32_bf16 v[42:45], v[142:145], v[196:199], v[42:45]
	v_mfma_f32_16x16x32_bf16 v[30:33], v[134:137], v[204:207], v[30:33]
	v_mfma_f32_16x16x32_bf16 v[26:29], v[142:145], v[204:207], v[26:29]
	v_mfma_f32_16x16x32_bf16 v[14:17], v[134:137], v[212:215], v[14:17]
	v_mfma_f32_16x16x32_bf16 v[10:13], v[142:145], v[212:215], v[10:13]
	s_setprio 0
	s_setprio 1
	v_mfma_f32_16x16x32_bf16 v[54:57], v[146:149], v[176:179], 0
	v_mfma_f32_16x16x32_bf16 v[50:53], v[154:157], v[176:179], 0
	v_mfma_f32_16x16x32_bf16 v[38:41], v[146:149], v[192:195], 0
	v_mfma_f32_16x16x32_bf16 v[34:37], v[154:157], v[192:195], 0
	v_mfma_f32_16x16x32_bf16 v[22:25], v[146:149], v[200:203], 0
	v_mfma_f32_16x16x32_bf16 v[18:21], v[154:157], v[200:203], 0
	v_mfma_f32_16x16x32_bf16 v[6:9], v[146:149], v[208:211], 0
	v_mfma_f32_16x16x32_bf16 v[2:5], v[154:157], v[208:211], 0
	v_mfma_f32_16x16x32_bf16 v[54:57], v[150:153], v[180:183], v[54:57]
	v_mfma_f32_16x16x32_bf16 v[50:53], v[172:175], v[180:183], v[50:53]
	v_mfma_f32_16x16x32_bf16 v[38:41], v[150:153], v[196:199], v[38:41]
	v_mfma_f32_16x16x32_bf16 v[34:37], v[172:175], v[196:199], v[34:37]
	v_mfma_f32_16x16x32_bf16 v[22:25], v[150:153], v[204:207], v[22:25]
	v_mfma_f32_16x16x32_bf16 v[18:21], v[172:175], v[204:207], v[18:21]
	v_mfma_f32_16x16x32_bf16 v[6:9], v[150:153], v[212:215], v[6:9]
	v_mfma_f32_16x16x32_bf16 v[2:5], v[172:175], v[212:215], v[2:5]
	s_setprio 0
	s_barrier
	s_add_i32 s24, 0, 0x18000
	s_add_i32 s55, 0, 0x1c000
	v_add_u32_e32 v142, s24, v188
	v_add_u32_e32 v171, s55, v188
	ds_read_b128 v[122:125], v142
	ds_read_b128 v[134:137], v142 offset:1024
	ds_read_b128 v[138:141], v142 offset:2048
	ds_read_b128 v[142:145], v142 offset:3072
	ds_read_b128 v[146:149], v171
	ds_read_b128 v[150:153], v171 offset:1024
	ds_read_b128 v[154:157], v171 offset:2048
	ds_read_b128 v[172:175], v171 offset:3072
	s_add_u32 s6, s52, s8
	s_addc_u32 s7, s53, 0
	s_mov_b32 m0, s59
	v_lshl_add_u64 v[226:227], s[6:7], 0, v[164:165]
	ds_read_b128 v[176:179], v190 offset:32768
	ds_read_b128 v[180:183], v190 offset:33792
	ds_read_b128 v[192:195], v190 offset:34816
	ds_read_b128 v[196:199], v190 offset:35840
	ds_read_b128 v[200:203], v190 offset:36864
	ds_read_b128 v[204:207], v190 offset:37888
	ds_read_b128 v[208:211], v190 offset:38912
	ds_read_b128 v[212:215], v190 offset:39936
	global_load_lds_dwordx4 v[226:227], off
	v_lshl_add_u64 v[226:227], s[6:7], 0, v[160:161]
	s_mov_b32 m0, s60
	s_nop 0
	global_load_lds_dwordx4 v[226:227], off
	s_waitcnt vmcnt(8)
	s_waitcnt lgkmcnt(0)
	s_barrier
	s_setprio 1
	s_waitcnt lgkmcnt(0)
	v_mfma_f32_16x16x32_bf16 v[130:133], v[122:125], v[176:179], v[130:133]
	v_mfma_f32_16x16x32_bf16 v[126:129], v[138:141], v[176:179], v[126:129]
	v_mfma_f32_16x16x32_bf16 v[110:113], v[122:125], v[192:195], v[110:113]
	v_mfma_f32_16x16x32_bf16 v[106:109], v[138:141], v[192:195], v[106:109]
	v_mfma_f32_16x16x32_bf16 v[94:97], v[122:125], v[200:203], v[94:97]
	v_mfma_f32_16x16x32_bf16 v[90:93], v[138:141], v[200:203], v[90:93]
	v_mfma_f32_16x16x32_bf16 v[78:81], v[122:125], v[208:211], v[78:81]
	v_mfma_f32_16x16x32_bf16 v[74:77], v[138:141], v[208:211], v[74:77]
	v_mfma_f32_16x16x32_bf16 v[130:133], v[134:137], v[180:183], v[130:133]
	v_mfma_f32_16x16x32_bf16 v[126:129], v[142:145], v[180:183], v[126:129]
	v_mfma_f32_16x16x32_bf16 v[110:113], v[134:137], v[196:199], v[110:113]
	v_mfma_f32_16x16x32_bf16 v[106:109], v[142:145], v[196:199], v[106:109]
	v_mfma_f32_16x16x32_bf16 v[94:97], v[134:137], v[204:207], v[94:97]
	v_mfma_f32_16x16x32_bf16 v[90:93], v[142:145], v[204:207], v[90:93]
	v_mfma_f32_16x16x32_bf16 v[78:81], v[134:137], v[212:215], v[78:81]
	v_mfma_f32_16x16x32_bf16 v[74:77], v[142:145], v[212:215], v[74:77]
	s_setprio 0
	s_setprio 1
	v_mfma_f32_16x16x32_bf16 v[118:121], v[146:149], v[176:179], v[118:121]
	v_mfma_f32_16x16x32_bf16 v[114:117], v[154:157], v[176:179], v[114:117]
	v_mfma_f32_16x16x32_bf16 v[102:105], v[146:149], v[192:195], v[102:105]
	v_mfma_f32_16x16x32_bf16 v[98:101], v[154:157], v[192:195], v[98:101]
	v_mfma_f32_16x16x32_bf16 v[86:89], v[146:149], v[200:203], v[86:89]
	v_mfma_f32_16x16x32_bf16 v[82:85], v[154:157], v[200:203], v[82:85]
	v_mfma_f32_16x16x32_bf16 v[70:73], v[146:149], v[208:211], v[70:73]
	v_mfma_f32_16x16x32_bf16 v[66:69], v[154:157], v[208:211], v[66:69]
	v_mfma_f32_16x16x32_bf16 v[118:121], v[150:153], v[180:183], v[118:121]
	v_mfma_f32_16x16x32_bf16 v[114:117], v[172:175], v[180:183], v[114:117]
	v_mfma_f32_16x16x32_bf16 v[102:105], v[150:153], v[196:199], v[102:105]
	v_mfma_f32_16x16x32_bf16 v[98:101], v[172:175], v[196:199], v[98:101]
	v_mfma_f32_16x16x32_bf16 v[86:89], v[150:153], v[204:207], v[86:89]
	v_mfma_f32_16x16x32_bf16 v[82:85], v[172:175], v[204:207], v[82:85]
	v_mfma_f32_16x16x32_bf16 v[70:73], v[150:153], v[212:215], v[70:73]
	v_mfma_f32_16x16x32_bf16 v[66:69], v[172:175], v[212:215], v[66:69]
	s_setprio 0
	s_barrier
	s_add_i32 s6, s24, s56
	v_lshl_add_u64 v[184:185], v[184:185], 0, s[84:85]
	s_mov_b32 m0, s6
	ds_read_b128 v[176:179], v190 offset:49152
	ds_read_b128 v[180:183], v190 offset:50176
	ds_read_b128 v[192:195], v190 offset:51200
	ds_read_b128 v[196:199], v190 offset:52224
	ds_read_b128 v[200:203], v190 offset:53248
	ds_read_b128 v[204:207], v190 offset:54272
	ds_read_b128 v[208:211], v190 offset:55296
	ds_read_b128 v[212:215], v190 offset:56320
	global_load_lds_dwordx4 v[184:185], off
	v_lshl_add_u64 v[184:185], v[216:217], 0, s[84:85]
	s_add_i32 m0, s6, 0x2000
	s_add_i32 s6, s55, s56
	global_load_lds_dwordx4 v[184:185], off
	v_lshl_add_u64 v[184:185], v[218:219], 0, s[84:85]
	s_mov_b32 m0, s6
	s_nop 0
	global_load_lds_dwordx4 v[184:185], off
	v_lshl_add_u64 v[184:185], v[220:221], 0, s[84:85]
	s_add_i32 m0, s6, 0x2000
	s_nop 0
	global_load_lds_dwordx4 v[184:185], off
	v_lshl_add_u64 v[184:185], v[222:223], 0, s[84:85]
	s_mov_b32 m0, s65
	s_nop 0
	global_load_lds_dwordx4 v[184:185], off
	v_lshl_add_u64 v[184:185], v[224:225], 0, s[84:85]
	s_mov_b32 m0, s66
	s_nop 0
	global_load_lds_dwordx4 v[184:185], off
	s_waitcnt vmcnt(8)
	s_waitcnt lgkmcnt(0)
	s_barrier
	s_setprio 1
	s_waitcnt lgkmcnt(0)
	v_mfma_f32_16x16x32_bf16 v[62:65], v[122:125], v[176:179], v[62:65]
	v_mfma_f32_16x16x32_bf16 v[58:61], v[138:141], v[176:179], v[58:61]
	v_mfma_f32_16x16x32_bf16 v[46:49], v[122:125], v[192:195], v[46:49]
	v_mfma_f32_16x16x32_bf16 v[42:45], v[138:141], v[192:195], v[42:45]
	v_mfma_f32_16x16x32_bf16 v[30:33], v[122:125], v[200:203], v[30:33]
	v_mfma_f32_16x16x32_bf16 v[26:29], v[138:141], v[200:203], v[26:29]
	v_mfma_f32_16x16x32_bf16 v[14:17], v[122:125], v[208:211], v[14:17]
	v_mfma_f32_16x16x32_bf16 v[10:13], v[138:141], v[208:211], v[10:13]
	v_mfma_f32_16x16x32_bf16 v[62:65], v[134:137], v[180:183], v[62:65]
	v_mfma_f32_16x16x32_bf16 v[58:61], v[142:145], v[180:183], v[58:61]
	v_mfma_f32_16x16x32_bf16 v[46:49], v[134:137], v[196:199], v[46:49]
	v_mfma_f32_16x16x32_bf16 v[42:45], v[142:145], v[196:199], v[42:45]
	v_mfma_f32_16x16x32_bf16 v[30:33], v[134:137], v[204:207], v[30:33]
	v_mfma_f32_16x16x32_bf16 v[26:29], v[142:145], v[204:207], v[26:29]
	v_mfma_f32_16x16x32_bf16 v[14:17], v[134:137], v[212:215], v[14:17]
	v_mfma_f32_16x16x32_bf16 v[10:13], v[142:145], v[212:215], v[10:13]
	s_setprio 0
	s_setprio 1
	v_mfma_f32_16x16x32_bf16 v[54:57], v[146:149], v[176:179], v[54:57]
	v_mfma_f32_16x16x32_bf16 v[50:53], v[154:157], v[176:179], v[50:53]
	v_mfma_f32_16x16x32_bf16 v[38:41], v[146:149], v[192:195], v[38:41]
	v_mfma_f32_16x16x32_bf16 v[34:37], v[154:157], v[192:195], v[34:37]
	v_mfma_f32_16x16x32_bf16 v[22:25], v[146:149], v[200:203], v[22:25]
	v_mfma_f32_16x16x32_bf16 v[18:21], v[154:157], v[200:203], v[18:21]
	v_mfma_f32_16x16x32_bf16 v[6:9], v[146:149], v[208:211], v[6:9]
	v_mfma_f32_16x16x32_bf16 v[2:5], v[154:157], v[208:211], v[2:5]
	v_mfma_f32_16x16x32_bf16 v[54:57], v[150:153], v[180:183], v[54:57]
	v_mfma_f32_16x16x32_bf16 v[50:53], v[172:175], v[180:183], v[50:53]
	v_mfma_f32_16x16x32_bf16 v[38:41], v[150:153], v[196:199], v[38:41]
	v_mfma_f32_16x16x32_bf16 v[34:37], v[172:175], v[196:199], v[34:37]
	v_mfma_f32_16x16x32_bf16 v[22:25], v[150:153], v[204:207], v[22:25]
	v_mfma_f32_16x16x32_bf16 v[18:21], v[172:175], v[204:207], v[18:21]
	v_mfma_f32_16x16x32_bf16 v[6:9], v[150:153], v[212:215], v[6:9]
	v_mfma_f32_16x16x32_bf16 v[2:5], v[172:175], v[212:215], v[2:5]
	s_setprio 0
	s_barrier
	s_add_u32 s50, s50, 0x100
	s_addc_u32 s51, s51, 0
	s_add_u32 s37, s37, 0x100
	s_addc_u32 s54, s54, 0
	s_cmp_ge_u32 s25, s62
	s_mov_b32 s24, s25
